# strategy 7: G2/G4 residual epilogue xor-32 row-sum step via v_permlane32_swap instead of ds_bpermute (16 LDS round trips removed), on stack22
# baseline (speedup 1.0000x reference)
; __device__ __forceinline__ unsigned cvt_pk_bf16(float lo, float hi) { unsigned r; asm volatile("v_cvt_pk_bf16_f32 %0, %1, %2" : "=v"(r) : "v"(lo), "v"(hi)); return r; }
;     __device__ __forceinline__ void operator()(const f32x4 (&acc)[2][2][4][2], const Unit& u, int wr, int wc, int fr, int fq) const {
;     ...
;             u32x4 pre[4][2];
; #pragma unroll
;             for (int m = 0; m < 4; ++m)
; #pragma unroll
;                 for (int bj = 0; bj < 2; ++bj) pre[m][bj] = *(const u32x4*)(xb + (size_t)(row0 + ai * HALF + m * 16) * 1024 + col0 + bj * HALF);
;             asm volatile("" ::: "memory");
; #pragma unroll
;             for (int m = 0; m < 4; ++m) {
;                 const int row = row0 + ai * HALF + m * 16; const size_t off = (size_t)row * 1024 + col0; float ss = 0.f;
; #pragma unroll
;                 for (int bj = 0; bj < 2; ++bj) {
;                     const u32x4 w = pre[m][bj];
;                     f32x4 v0 = acc[ai][bj][m][0], v1 = acc[ai][bj][m][1];
;                     v0[0] += __uint_as_float(w.x << 16); v0[1] += __uint_as_float(w.x & 0xffff0000u); v0[2] += __uint_as_float(w.y << 16); v0[3] += __uint_as_float(w.y & 0xffff0000u);
;                     v1[0] += __uint_as_float(w.z << 16); v1[1] += __uint_as_float(w.z & 0xffff0000u); v1[2] += __uint_as_float(w.w << 16); v1[3] += __uint_as_float(w.w & 0xffff0000u);
;                     if (outf) { *(f32x4*)(outf + off + bj * HALF) = v0; *(f32x4*)(outf + off + bj * HALF + 4) = v1; }
;                     else {
;                         ss += ((v0[0] * v0[0] + v0[1] * v0[1]) + (v0[2] * v0[2] + v0[3] * v0[3])) + ((v1[0] * v1[0] + v1[1] * v1[1]) + (v1[2] * v1[2] + v1[3] * v1[3]));
;                         u32x4 o; o.x = cvt_pk_bf16(v0[0], v0[1]); o.y = cvt_pk_bf16(v0[2], v0[3]); o.z = cvt_pk_bf16(v1[0], v1[1]); o.w = cvt_pk_bf16(v1[2], v1[3]);
;                         *(u32x4*)(xb + off + bj * HALF) = o;
;                     }
;                 }
;                 if (!outf) { ss += __shfl_xor(ss, 16); ss += __shfl_xor(ss, 32); if (fq == 0) rowsq[(size_t)row * 16 + u.pn * 4 + wc] = ss; }
.LBB0_561:
	v_lshl_or_b32 v164, s14, 8, v202
	v_lshl_add_u32 v168, s31, 8, v200
	v_ashrrev_i32_e32 v165, 31, v164
	v_lshlrev_b64 v[178:179], 1, v[164:165]
	v_ashrrev_i32_e32 v169, 31, v168
	v_lshl_add_u64 v[166:167], s[8:9], 0, v[178:179]
	v_lshlrev_b64 v[212:213], 11, v[168:169]
	v_lshl_add_u64 v[112:113], v[166:167], 0, v[212:213]
	flat_load_dwordx4 v[204:207], v[112:113]
	flat_load_dwordx4 v[208:211], v[112:113] offset:256
	v_or_b32_e32 v196, 16, v168
	v_ashrrev_i32_e32 v197, 31, v196
	v_or_b32_e32 v174, 32, v168
	v_lshlrev_b64 v[198:199], 11, v[196:197]
	v_ashrrev_i32_e32 v175, 31, v174
	v_or_b32_e32 v170, 48, v168
	v_lshl_add_u64 v[112:113], v[166:167], 0, v[198:199]
	v_lshlrev_b64 v[194:195], 11, v[174:175]
	v_ashrrev_i32_e32 v171, 31, v170
	flat_load_dwordx4 v[132:135], v[112:113]
	flat_load_dwordx4 v[128:131], v[112:113] offset:256
	v_lshl_add_u64 v[112:113], v[166:167], 0, v[194:195]
	v_lshlrev_b64 v[172:173], 11, v[170:171]
	flat_load_dwordx4 v[124:127], v[112:113]
	flat_load_dwordx4 v[120:123], v[112:113] offset:256
	v_lshl_add_u64 v[112:113], v[166:167], 0, v[172:173]
	flat_load_dwordx4 v[116:119], v[112:113]
	s_nop 0
	flat_load_dwordx4 v[112:115], v[112:113] offset:256
	v_add_u32_e32 v236, 0x80, v168
	v_ashrrev_i32_e32 v237, 31, v236
	v_lshlrev_b64 v[236:237], 11, v[236:237]
	v_lshl_add_u64 v[236:237], v[166:167], 0, v[236:237]
	flat_load_dwordx4 v[216:219], v[236:237]
	flat_load_dwordx4 v[220:223], v[236:237] offset:256
	v_add_u32_e32 v236, 0x90, v168
	v_ashrrev_i32_e32 v237, 31, v236
	v_lshlrev_b64 v[236:237], 11, v[236:237]
	v_lshl_add_u64 v[236:237], v[166:167], 0, v[236:237]
	flat_load_dwordx4 v[224:227], v[236:237]
	flat_load_dwordx4 v[228:231], v[236:237] offset:256
	v_add_u32_e32 v236, 0xa0, v168
	v_ashrrev_i32_e32 v237, 31, v236
	v_lshlrev_b64 v[236:237], 11, v[236:237]
	v_lshl_add_u64 v[236:237], v[166:167], 0, v[236:237]
	flat_load_dwordx4 v[232:235], v[236:237]
	flat_load_dwordx4 v[152:155], v[236:237] offset:256
	v_add_u32_e32 v236, 0xb0, v168
	v_ashrrev_i32_e32 v237, 31, v236
	v_lshlrev_b64 v[236:237], 11, v[236:237]
	v_lshl_add_u64 v[236:237], v[166:167], 0, v[236:237]
	flat_load_dwordx4 v[156:159], v[236:237]
	flat_load_dwordx4 v[160:163], v[236:237] offset:256
	s_lshl_b32 s48, s14, 2
	s_ashr_i32 s49, s48, 31
	s_waitcnt vmcnt(0) lgkmcnt(0)
	v_lshlrev_b32_e32 v214, 16, v204
	v_and_b32_e32 v204, 0xffff0000, v204
	v_add_f32_e32 v149, v149, v204
	v_lshlrev_b32_e32 v204, 16, v205
	v_add_f32_e32 v150, v150, v204
	v_and_b32_e32 v204, 0xffff0000, v205
	v_add_f32_e32 v151, v151, v204
	v_lshlrev_b32_e32 v204, 16, v206
	v_add_f32_e32 v204, v144, v204
	v_and_b32_e32 v144, 0xffff0000, v206
	v_add_f32_e32 v205, v145, v144
	v_lshlrev_b32_e32 v144, 16, v207
	v_add_f32_e32 v206, v146, v144
	v_and_b32_e32 v144, 0xffff0000, v207
	v_add_f32_e32 v148, v148, v214
	v_add_f32_e32 v147, v147, v144
	v_mul_f32_e32 v144, v149, v149
	v_mul_f32_e32 v145, v151, v151
	v_fmac_f32_e32 v144, v148, v148
	v_fmac_f32_e32 v145, v150, v150
	v_add_f32_e32 v144, v144, v145
	v_mul_f32_e32 v145, v205, v205
	v_mul_f32_e32 v146, v147, v147
	v_fmac_f32_e32 v145, v204, v204
	v_fmac_f32_e32 v146, v206, v206
	v_add_f32_e32 v145, v145, v146
	v_add_f32_e32 v207, v144, v145
	v_cvt_pk_bf16_f32 v144, v148, v149
	v_lshl_add_u64 v[148:149], s[8:9], 0, v[212:213]
	v_lshl_add_u64 v[148:149], v[148:149], 0, v[178:179]
	v_cvt_pk_bf16_f32 v145, v150, v151
	v_cvt_pk_bf16_f32 v146, v204, v205
	v_cvt_pk_bf16_f32 v147, v206, v147
	flat_store_dwordx4 v[148:149], v[144:147]
	s_nop 1
	v_lshlrev_b32_e32 v144, 16, v208
	v_add_f32_e32 v140, v140, v144
	v_and_b32_e32 v144, 0xffff0000, v208
	v_add_f32_e32 v141, v141, v144
	v_lshlrev_b32_e32 v144, 16, v209
	v_add_f32_e32 v142, v142, v144
	v_and_b32_e32 v144, 0xffff0000, v209
	v_add_f32_e32 v143, v143, v144
	v_lshlrev_b32_e32 v144, 16, v210
	v_add_f32_e32 v136, v136, v144
	v_and_b32_e32 v144, 0xffff0000, v210
	v_add_f32_e32 v144, v137, v144
	v_lshlrev_b32_e32 v137, 16, v211
	v_add_f32_e32 v145, v138, v137
	v_and_b32_e32 v137, 0xffff0000, v211
	v_add_f32_e32 v146, v139, v137
	v_mul_f32_e32 v137, v141, v141
	v_mul_f32_e32 v138, v143, v143
	v_fmac_f32_e32 v137, v140, v140
	v_fmac_f32_e32 v138, v142, v142
	v_add_f32_e32 v137, v137, v138
	v_mul_f32_e32 v138, v144, v144
	v_mul_f32_e32 v139, v146, v146
	v_fmac_f32_e32 v138, v136, v136
	v_fmac_f32_e32 v139, v145, v145
	v_add_f32_e32 v138, v138, v139
	v_add_f32_e32 v137, v137, v138
	v_cvt_pk_bf16_f32 v138, v140, v141
	v_cvt_pk_bf16_f32 v139, v142, v143
	v_cvt_pk_bf16_f32 v140, v136, v144
	v_cvt_pk_bf16_f32 v141, v145, v146
	flat_store_dwordx4 v[148:149], v[138:141] offset:256
	v_xor_b32_e32 v136, 16, v244
	v_add_f32_e32 v137, v207, v137
	v_and_b32_e32 v138, 64, v244
	v_add_u32_e32 v139, 64, v138
	v_cmp_lt_i32_e32 vcc, v136, v139
	s_nop 1
	v_cndmask_b32_e32 v136, v244, v136, vcc
	v_lshlrev_b32_e32 v136, 2, v136
	ds_bpermute_b32 v138, v136, v137
	s_waitcnt lgkmcnt(0)
	v_add_f32_e32 v138, v137, v138
	v_xor_b32_e32 v137, 32, v244
	v_cmp_lt_i32_e32 vcc, v137, v139
	s_nop 1
	v_cndmask_b32_e32 v137, v244, v137, vcc
	v_lshlrev_b32_e32 v137, 2, v137
	v_mov_b32_e32 v139, v138
	s_nop 1
	v_permlane32_swap_b32_e32 v138, v139
	s_and_saveexec_b64 s[34:35], s[0:1]
	s_cbranch_execz .LBB0_563
	v_lshlrev_b64 v[140:141], 6, v[168:169]
	v_readlane_b32 s14, v254, 24
	v_lshl_add_u64 v[140:141], s[16:17], 0, v[140:141]
	v_readlane_b32 s15, v254, 25
	v_lshl_add_u64 v[140:141], s[48:49], 2, v[140:141]
	s_mov_b32 s19, s15
	s_lshl_b32 s18, s25, 2
	v_writelane_b32 v254, s14, 24
	v_lshl_add_u64 v[140:141], v[140:141], 0, s[18:19]
	s_waitcnt lgkmcnt(0)
	v_add_f32_e32 v138, v138, v139
	v_writelane_b32 v254, s15, 25
	flat_store_dword v[140:141], v138
; __device__ __forceinline__ unsigned cvt_pk_bf16(float lo, float hi) { unsigned r; asm volatile("v_cvt_pk_bf16_f32 %0, %1, %2" : "=v"(r) : "v"(lo), "v"(hi)); return r; }
;     __device__ __forceinline__ void operator()(const f32x4 (&acc)[2][2][4][2], const Unit& u, int wr, int wc, int fr, int fq) const {
;     ...
;             for (int m = 0; m < 4; ++m) {
;                 const int row = row0 + ai * HALF + m * 16; const size_t off = (size_t)row * 1024 + col0; float ss = 0.f;
; #pragma unroll
;                 for (int bj = 0; bj < 2; ++bj) {
;                     const u32x4 w = pre[m][bj];
;                     f32x4 v0 = acc[ai][bj][m][0], v1 = acc[ai][bj][m][1];
;                     v0[0] += __uint_as_float(w.x << 16); v0[1] += __uint_as_float(w.x & 0xffff0000u); v0[2] += __uint_as_float(w.y << 16); v0[3] += __uint_as_float(w.y & 0xffff0000u);
;                     v1[0] += __uint_as_float(w.z << 16); v1[1] += __uint_as_float(w.z & 0xffff0000u); v1[2] += __uint_as_float(w.w << 16); v1[3] += __uint_as_float(w.w & 0xffff0000u);
;                     if (outf) { *(f32x4*)(outf + off + bj * HALF) = v0; *(f32x4*)(outf + off + bj * HALF + 4) = v1; }
;                     else {
;                         ss += ((v0[0] * v0[0] + v0[1] * v0[1]) + (v0[2] * v0[2] + v0[3] * v0[3])) + ((v1[0] * v1[0] + v1[1] * v1[1]) + (v1[2] * v1[2] + v1[3] * v1[3]));
;                         u32x4 o; o.x = cvt_pk_bf16(v0[0], v0[1]); o.y = cvt_pk_bf16(v0[2], v0[3]); o.z = cvt_pk_bf16(v1[0], v1[1]); o.w = cvt_pk_bf16(v1[2], v1[3]);
;                         *(u32x4*)(xb + off + bj * HALF) = o;
;                     }
;                 }
;                 if (!outf) { ss += __shfl_xor(ss, 16); ss += __shfl_xor(ss, 32); if (fq == 0) rowsq[(size_t)row * 16 + u.pn * 4 + wc] = ss; }
.LBB0_563:
	s_or_b64 exec, exec, s[34:35]
	v_lshlrev_b32_e32 v138, 16, v132
	v_and_b32_e32 v132, 0xffff0000, v132
	v_add_f32_e32 v109, v109, v132
	v_lshlrev_b32_e32 v132, 16, v133
	v_add_f32_e32 v110, v110, v132
	v_and_b32_e32 v132, 0xffff0000, v133
	v_add_f32_e32 v111, v111, v132
	v_lshlrev_b32_e32 v132, 16, v134
	v_add_f32_e32 v132, v104, v132
	v_and_b32_e32 v104, 0xffff0000, v134
	v_add_f32_e32 v133, v105, v104
	v_lshlrev_b32_e32 v104, 16, v135
	v_add_f32_e32 v134, v106, v104
	v_and_b32_e32 v104, 0xffff0000, v135
	v_add_f32_e32 v108, v108, v138
	v_add_f32_e32 v107, v107, v104
	v_mul_f32_e32 v104, v109, v109
	v_mul_f32_e32 v105, v111, v111
	v_fmac_f32_e32 v104, v108, v108
	v_fmac_f32_e32 v105, v110, v110
	v_add_f32_e32 v104, v104, v105
	v_mul_f32_e32 v105, v133, v133
	v_mul_f32_e32 v106, v107, v107
	v_fmac_f32_e32 v105, v132, v132
	v_fmac_f32_e32 v106, v134, v134
	v_add_f32_e32 v105, v105, v106
	v_add_f32_e32 v135, v104, v105
	v_cvt_pk_bf16_f32 v104, v108, v109
	v_lshlrev_b32_e32 v108, 16, v128
	v_add_f32_e32 v100, v100, v108
	v_and_b32_e32 v108, 0xffff0000, v128
	v_add_f32_e32 v101, v101, v108
	v_lshlrev_b32_e32 v108, 16, v129
	v_add_f32_e32 v108, v102, v108
	v_and_b32_e32 v102, 0xffff0000, v129
	v_add_f32_e32 v109, v103, v102
	v_lshlrev_b32_e32 v102, 16, v130
	v_cvt_pk_bf16_f32 v105, v110, v111
	v_add_f32_e32 v110, v96, v102
	v_and_b32_e32 v96, 0xffff0000, v130
	v_add_f32_e32 v111, v97, v96
	v_lshlrev_b32_e32 v96, 16, v131
	v_add_f32_e32 v128, v98, v96
	v_and_b32_e32 v96, 0xffff0000, v131
	v_add_f32_e32 v129, v99, v96
	v_mul_f32_e32 v96, v101, v101
	v_mul_f32_e32 v97, v109, v109
	v_fmac_f32_e32 v96, v100, v100
	v_fmac_f32_e32 v97, v108, v108
	v_add_f32_e32 v96, v96, v97
	v_mul_f32_e32 v97, v111, v111
	v_mul_f32_e32 v98, v129, v129
	v_fmac_f32_e32 v97, v110, v110
	v_fmac_f32_e32 v98, v128, v128
	v_add_f32_e32 v97, v97, v98
	v_add_f32_e32 v96, v96, v97
	v_add_f32_e32 v99, v135, v96
	ds_bpermute_b32 v130, v136, v99
	v_lshl_add_u64 v[96:97], s[8:9], 0, v[198:199]
	v_lshl_add_u64 v[102:103], v[164:165], 1, v[96:97]
	v_cvt_pk_bf16_f32 v106, v132, v133
	v_cvt_pk_bf16_f32 v107, v134, v107
	s_waitcnt lgkmcnt(0)
	v_add_f32_e32 v96, v99, v130
	v_mov_b32_e32 v97, v96
	s_nop 1
	v_permlane32_swap_b32_e32 v96, v97
	flat_store_dwordx4 v[102:103], v[104:107]
	v_cvt_pk_bf16_f32 v98, v100, v101
	v_cvt_pk_bf16_f32 v99, v108, v109
	v_cvt_pk_bf16_f32 v100, v110, v111
	v_cvt_pk_bf16_f32 v101, v128, v129
	flat_store_dwordx4 v[102:103], v[98:101] offset:256
	s_and_saveexec_b64 s[34:35], s[0:1]
	s_cbranch_execz .LBB0_565
	v_lshlrev_b64 v[98:99], 6, v[196:197]
	v_readlane_b32 s14, v254, 24
	v_lshl_add_u64 v[98:99], s[16:17], 0, v[98:99]
	v_readlane_b32 s15, v254, 25
	v_lshl_add_u64 v[98:99], s[48:49], 2, v[98:99]
	s_mov_b32 s19, s15
	s_lshl_b32 s18, s25, 2
	v_writelane_b32 v254, s14, 24
	v_lshl_add_u64 v[98:99], v[98:99], 0, s[18:19]
	s_waitcnt lgkmcnt(0)
	v_add_f32_e32 v96, v96, v97
	v_writelane_b32 v254, s15, 25
	flat_store_dword v[98:99], v96
.LBB0_565:
	s_or_b64 exec, exec, s[34:35]
	v_lshlrev_b32_e32 v96, 16, v124
	v_add_f32_e32 v92, v92, v96
	v_and_b32_e32 v96, 0xffff0000, v124
	v_add_f32_e32 v93, v93, v96
	v_lshlrev_b32_e32 v96, 16, v125
	v_add_f32_e32 v94, v94, v96
	v_and_b32_e32 v96, 0xffff0000, v125
	v_add_f32_e32 v95, v95, v96
	v_lshlrev_b32_e32 v96, 16, v126
	v_add_f32_e32 v96, v88, v96
	v_and_b32_e32 v88, 0xffff0000, v126
	s_waitcnt lgkmcnt(0)
	v_add_f32_e32 v97, v89, v88
	v_lshlrev_b32_e32 v88, 16, v127
	v_add_f32_e32 v98, v90, v88
	v_and_b32_e32 v88, 0xffff0000, v127
	v_add_f32_e32 v91, v91, v88
	v_mul_f32_e32 v88, v93, v93
	v_mul_f32_e32 v89, v95, v95
	v_fmac_f32_e32 v88, v92, v92
	v_fmac_f32_e32 v89, v94, v94
	v_add_f32_e32 v88, v88, v89
	v_mul_f32_e32 v89, v97, v97
	v_mul_f32_e32 v90, v91, v91
	v_fmac_f32_e32 v89, v96, v96
	v_fmac_f32_e32 v90, v98, v98
	v_add_f32_e32 v89, v89, v90
	v_add_f32_e32 v99, v88, v89
	v_cvt_pk_bf16_f32 v88, v92, v93
	v_lshlrev_b32_e32 v92, 16, v120
	v_add_f32_e32 v84, v84, v92
	v_and_b32_e32 v92, 0xffff0000, v120
	v_add_f32_e32 v85, v85, v92
	v_lshlrev_b32_e32 v92, 16, v121
	v_add_f32_e32 v92, v86, v92
	v_and_b32_e32 v86, 0xffff0000, v121
	v_add_f32_e32 v93, v87, v86
	v_lshlrev_b32_e32 v86, 16, v122
	v_cvt_pk_bf16_f32 v89, v94, v95
	v_add_f32_e32 v94, v80, v86
	v_and_b32_e32 v80, 0xffff0000, v122
	v_add_f32_e32 v95, v81, v80
	v_lshlrev_b32_e32 v80, 16, v123
	v_cvt_pk_bf16_f32 v90, v96, v97
	v_add_f32_e32 v96, v82, v80
	v_and_b32_e32 v80, 0xffff0000, v123
	v_add_f32_e32 v97, v83, v80
	v_mul_f32_e32 v80, v85, v85
	v_mul_f32_e32 v81, v93, v93
	v_fmac_f32_e32 v80, v84, v84
	v_fmac_f32_e32 v81, v92, v92
	v_add_f32_e32 v80, v80, v81
	v_mul_f32_e32 v81, v95, v95
	v_mul_f32_e32 v82, v97, v97
	v_fmac_f32_e32 v81, v94, v94
	v_fmac_f32_e32 v82, v96, v96
	v_add_f32_e32 v81, v81, v82
	v_add_f32_e32 v80, v80, v81
	v_add_f32_e32 v83, v99, v80
	v_cvt_pk_bf16_f32 v91, v98, v91
	ds_bpermute_b32 v98, v136, v83
	v_lshl_add_u64 v[80:81], s[8:9], 0, v[194:195]
	v_lshl_add_u64 v[86:87], v[164:165], 1, v[80:81]
	flat_store_dwordx4 v[86:87], v[88:91]
	v_cvt_pk_bf16_f32 v82, v84, v85
	s_waitcnt lgkmcnt(0)
	v_add_f32_e32 v80, v83, v98
	v_mov_b32_e32 v81, v80
	s_nop 1
	v_permlane32_swap_b32_e32 v80, v81
	v_cvt_pk_bf16_f32 v83, v92, v93
	v_cvt_pk_bf16_f32 v84, v94, v95
	v_cvt_pk_bf16_f32 v85, v96, v97
	flat_store_dwordx4 v[86:87], v[82:85] offset:256
	s_and_saveexec_b64 s[34:35], s[0:1]
	s_cbranch_execz .LBB0_567
	v_lshlrev_b64 v[82:83], 6, v[174:175]
	v_readlane_b32 s14, v254, 24
	v_lshl_add_u64 v[82:83], s[16:17], 0, v[82:83]
	v_readlane_b32 s15, v254, 25
	v_lshl_add_u64 v[82:83], s[48:49], 2, v[82:83]
	s_mov_b32 s19, s15
	s_lshl_b32 s18, s25, 2
	v_writelane_b32 v254, s14, 24
	v_lshl_add_u64 v[82:83], v[82:83], 0, s[18:19]
	s_waitcnt lgkmcnt(0)
	v_add_f32_e32 v80, v80, v81
	v_writelane_b32 v254, s15, 25
	flat_store_dword v[82:83], v80
; __device__ __forceinline__ unsigned cvt_pk_bf16(float lo, float hi) { unsigned r; asm volatile("v_cvt_pk_bf16_f32 %0, %1, %2" : "=v"(r) : "v"(lo), "v"(hi)); return r; }
;     __device__ __forceinline__ void operator()(const f32x4 (&acc)[2][2][4][2], const Unit& u, int wr, int wc, int fr, int fq) const {
;     ...
;             for (int m = 0; m < 4; ++m) {
;                 const int row = row0 + ai * HALF + m * 16; const size_t off = (size_t)row * 1024 + col0; float ss = 0.f;
; #pragma unroll
;                 for (int bj = 0; bj < 2; ++bj) {
;                     const u32x4 w = pre[m][bj];
;                     f32x4 v0 = acc[ai][bj][m][0], v1 = acc[ai][bj][m][1];
;                     v0[0] += __uint_as_float(w.x << 16); v0[1] += __uint_as_float(w.x & 0xffff0000u); v0[2] += __uint_as_float(w.y << 16); v0[3] += __uint_as_float(w.y & 0xffff0000u);
;                     v1[0] += __uint_as_float(w.z << 16); v1[1] += __uint_as_float(w.z & 0xffff0000u); v1[2] += __uint_as_float(w.w << 16); v1[3] += __uint_as_float(w.w & 0xffff0000u);
;                     if (outf) { *(f32x4*)(outf + off + bj * HALF) = v0; *(f32x4*)(outf + off + bj * HALF + 4) = v1; }
;                     else {
;                         ss += ((v0[0] * v0[0] + v0[1] * v0[1]) + (v0[2] * v0[2] + v0[3] * v0[3])) + ((v1[0] * v1[0] + v1[1] * v1[1]) + (v1[2] * v1[2] + v1[3] * v1[3]));
;                         u32x4 o; o.x = cvt_pk_bf16(v0[0], v0[1]); o.y = cvt_pk_bf16(v0[2], v0[3]); o.z = cvt_pk_bf16(v1[0], v1[1]); o.w = cvt_pk_bf16(v1[2], v1[3]);
;                         *(u32x4*)(xb + off + bj * HALF) = o;
;                     }
;                 }
;                 if (!outf) { ss += __shfl_xor(ss, 16); ss += __shfl_xor(ss, 32); if (fq == 0) rowsq[(size_t)row * 16 + u.pn * 4 + wc] = ss; }
.LBB0_567:
	s_or_b64 exec, exec, s[34:35]
	v_lshlrev_b32_e32 v80, 16, v116
	v_add_f32_e32 v76, v76, v80
	v_and_b32_e32 v80, 0xffff0000, v116
	v_add_f32_e32 v77, v77, v80
	v_lshlrev_b32_e32 v80, 16, v117
	v_add_f32_e32 v78, v78, v80
	v_and_b32_e32 v80, 0xffff0000, v117
	v_add_f32_e32 v79, v79, v80
	v_lshlrev_b32_e32 v80, 16, v118
	v_add_f32_e32 v80, v72, v80
	v_and_b32_e32 v72, 0xffff0000, v118
	s_waitcnt lgkmcnt(0)
	v_add_f32_e32 v81, v73, v72
	v_lshlrev_b32_e32 v72, 16, v119
	v_add_f32_e32 v82, v74, v72
	v_and_b32_e32 v72, 0xffff0000, v119
	v_add_f32_e32 v75, v75, v72
	v_mul_f32_e32 v72, v77, v77
	v_mul_f32_e32 v73, v79, v79
	v_fmac_f32_e32 v72, v76, v76
	v_fmac_f32_e32 v73, v78, v78
	v_add_f32_e32 v72, v72, v73
	v_mul_f32_e32 v73, v81, v81
	v_mul_f32_e32 v74, v75, v75
	v_fmac_f32_e32 v73, v80, v80
	v_fmac_f32_e32 v74, v82, v82
	v_add_f32_e32 v73, v73, v74
	v_add_f32_e32 v83, v72, v73
	v_cvt_pk_bf16_f32 v72, v76, v77
	v_lshlrev_b32_e32 v76, 16, v112
	v_add_f32_e32 v68, v68, v76
	v_and_b32_e32 v76, 0xffff0000, v112
	v_add_f32_e32 v69, v69, v76
	v_lshlrev_b32_e32 v76, 16, v113
	v_add_f32_e32 v76, v70, v76
	v_and_b32_e32 v70, 0xffff0000, v113
	v_add_f32_e32 v77, v71, v70
	v_lshlrev_b32_e32 v70, 16, v114
	v_cvt_pk_bf16_f32 v73, v78, v79
	v_add_f32_e32 v78, v64, v70
	v_and_b32_e32 v64, 0xffff0000, v114
	v_add_f32_e32 v79, v65, v64
	v_lshlrev_b32_e32 v64, 16, v115
	v_cvt_pk_bf16_f32 v74, v80, v81
	v_add_f32_e32 v80, v66, v64
	v_and_b32_e32 v64, 0xffff0000, v115
	v_add_f32_e32 v81, v67, v64
	v_mul_f32_e32 v64, v69, v69
	v_mul_f32_e32 v65, v77, v77
	v_fmac_f32_e32 v64, v68, v68
	v_fmac_f32_e32 v65, v76, v76
	v_add_f32_e32 v64, v64, v65
	v_mul_f32_e32 v65, v79, v79
	v_mul_f32_e32 v66, v81, v81
	v_fmac_f32_e32 v65, v78, v78
	v_fmac_f32_e32 v66, v80, v80
	v_add_f32_e32 v65, v65, v66
	v_add_f32_e32 v64, v64, v65
	v_add_f32_e32 v67, v83, v64
	v_cvt_pk_bf16_f32 v75, v82, v75
	ds_bpermute_b32 v82, v136, v67
	v_lshl_add_u64 v[64:65], s[8:9], 0, v[172:173]
	v_lshl_add_u64 v[70:71], v[164:165], 1, v[64:65]
	flat_store_dwordx4 v[70:71], v[72:75]
	v_cvt_pk_bf16_f32 v66, v68, v69
	s_waitcnt lgkmcnt(0)
	v_add_f32_e32 v64, v67, v82
	v_mov_b32_e32 v65, v64
	s_nop 1
	v_permlane32_swap_b32_e32 v64, v65
	v_cvt_pk_bf16_f32 v67, v76, v77
	v_cvt_pk_bf16_f32 v68, v78, v79
	v_cvt_pk_bf16_f32 v69, v80, v81
	flat_store_dwordx4 v[70:71], v[66:69] offset:256
	s_and_saveexec_b64 s[34:35], s[0:1]
	s_cbranch_execz .LBB0_569
	v_lshlrev_b64 v[66:67], 6, v[170:171]
	v_readlane_b32 s14, v254, 24
	v_lshl_add_u64 v[66:67], s[16:17], 0, v[66:67]
	v_readlane_b32 s15, v254, 25
	v_lshl_add_u64 v[66:67], s[48:49], 2, v[66:67]
	s_mov_b32 s19, s15
	s_lshl_b32 s18, s25, 2
	v_writelane_b32 v254, s14, 24
	v_lshl_add_u64 v[66:67], v[66:67], 0, s[18:19]
	s_waitcnt lgkmcnt(0)
	v_add_f32_e32 v64, v64, v65
	v_writelane_b32 v254, s15, 25
	flat_store_dword v[66:67], v64
.LBB0_569:
	s_or_b64 exec, exec, s[34:35]
	v_add_u32_e32 v104, 0x80, v168
	v_ashrrev_i32_e32 v105, 31, v104
	v_lshlrev_b64 v[110:111], 11, v[104:105]
	s_waitcnt lgkmcnt(0)
	v_lshl_add_u64 v[64:65], v[166:167], 0, v[110:111]
	v_add_u32_e32 v100, 0x90, v168
	v_ashrrev_i32_e32 v101, 31, v100
	v_add_u32_e32 v96, 0xa0, v168
	v_lshlrev_b64 v[102:103], 11, v[100:101]
	v_ashrrev_i32_e32 v97, 31, v96
	v_add_u32_e32 v92, 0xb0, v168
	v_lshl_add_u64 v[64:65], v[166:167], 0, v[102:103]
	v_lshlrev_b64 v[98:99], 11, v[96:97]
	v_ashrrev_i32_e32 v93, 31, v92
	v_lshl_add_u64 v[64:65], v[166:167], 0, v[98:99]
	v_lshlrev_b64 v[94:95], 11, v[92:93]
	v_lshl_add_u64 v[64:65], v[166:167], 0, v[94:95]
	v_lshlrev_b32_e32 v112, 16, v216
	v_and_b32_e32 v106, 0xffff0000, v216
	v_add_f32_e32 v61, v61, v106
	v_lshlrev_b32_e32 v106, 16, v217
	v_add_f32_e32 v62, v62, v106
	v_and_b32_e32 v106, 0xffff0000, v217
	v_add_f32_e32 v63, v63, v106
	v_lshlrev_b32_e32 v106, 16, v218
	v_add_f32_e32 v56, v56, v106
	v_and_b32_e32 v106, 0xffff0000, v218
	v_add_f32_e32 v57, v57, v106
	v_lshlrev_b32_e32 v106, 16, v219
	v_add_f32_e32 v106, v58, v106
	v_and_b32_e32 v58, 0xffff0000, v219
	v_add_f32_e32 v60, v60, v112
	v_add_f32_e32 v107, v59, v58
	v_mul_f32_e32 v58, v61, v61
	v_mul_f32_e32 v59, v63, v63
	v_fmac_f32_e32 v58, v60, v60
	v_fmac_f32_e32 v59, v62, v62
	v_add_f32_e32 v58, v58, v59
	v_mul_f32_e32 v59, v57, v57
	v_mul_f32_e32 v108, v107, v107
	v_fmac_f32_e32 v59, v56, v56
	v_fmac_f32_e32 v108, v106, v106
	v_add_f32_e32 v59, v59, v108
	v_add_f32_e32 v108, v58, v59
	v_cvt_pk_bf16_f32 v58, v60, v61
	v_cvt_pk_bf16_f32 v59, v62, v63
	v_cvt_pk_bf16_f32 v60, v56, v57
	v_lshl_add_u64 v[56:57], s[8:9], 0, v[110:111]
	v_lshl_add_u64 v[56:57], v[164:165], 1, v[56:57]
	v_cvt_pk_bf16_f32 v61, v106, v107
	flat_store_dwordx4 v[56:57], v[58:61]
	s_nop 1
	v_lshlrev_b32_e32 v58, 16, v220
	v_add_f32_e32 v52, v52, v58
	v_and_b32_e32 v58, 0xffff0000, v220
	v_add_f32_e32 v53, v53, v58
	v_lshlrev_b32_e32 v58, 16, v221
	v_add_f32_e32 v54, v54, v58
	v_and_b32_e32 v58, 0xffff0000, v221
	v_add_f32_e32 v55, v55, v58
	v_lshlrev_b32_e32 v58, 16, v222
	v_add_f32_e32 v58, v48, v58
	v_and_b32_e32 v48, 0xffff0000, v222
	v_add_f32_e32 v59, v49, v48
	v_lshlrev_b32_e32 v48, 16, v223
	v_add_f32_e32 v60, v50, v48
	v_and_b32_e32 v48, 0xffff0000, v223
	v_add_f32_e32 v51, v51, v48
	v_mul_f32_e32 v48, v53, v53
	v_mul_f32_e32 v49, v55, v55
	v_fmac_f32_e32 v48, v52, v52
	v_fmac_f32_e32 v49, v54, v54
	v_add_f32_e32 v48, v48, v49
	v_mul_f32_e32 v49, v59, v59
	v_mul_f32_e32 v50, v51, v51
	v_fmac_f32_e32 v49, v58, v58
	v_fmac_f32_e32 v50, v60, v60
	v_add_f32_e32 v49, v49, v50
	v_add_f32_e32 v48, v48, v49
	v_add_f32_e32 v61, v108, v48
	v_cvt_pk_bf16_f32 v48, v52, v53
	v_cvt_pk_bf16_f32 v49, v54, v55
	v_cvt_pk_bf16_f32 v50, v58, v59
	v_cvt_pk_bf16_f32 v51, v60, v51
	flat_store_dwordx4 v[56:57], v[48:51] offset:256
	ds_bpermute_b32 v48, v136, v61
	s_waitcnt lgkmcnt(0)
	v_add_f32_e32 v48, v61, v48
	v_mov_b32_e32 v49, v48
	s_nop 1
	v_permlane32_swap_b32_e32 v48, v49
	s_and_saveexec_b64 s[34:35], s[0:1]
	s_cbranch_execz .LBB0_571
	v_lshlrev_b64 v[50:51], 6, v[104:105]
	v_readlane_b32 s14, v254, 24
	v_lshl_add_u64 v[50:51], s[16:17], 0, v[50:51]
	v_readlane_b32 s15, v254, 25
	v_lshl_add_u64 v[50:51], s[48:49], 2, v[50:51]
	s_mov_b32 s19, s15
	s_lshl_b32 s18, s25, 2
	v_writelane_b32 v254, s14, 24
	v_lshl_add_u64 v[50:51], v[50:51], 0, s[18:19]
	s_waitcnt lgkmcnt(0)
	v_add_f32_e32 v48, v48, v49
	v_writelane_b32 v254, s15, 25
	flat_store_dword v[50:51], v48
; __device__ __forceinline__ unsigned cvt_pk_bf16(float lo, float hi) { unsigned r; asm volatile("v_cvt_pk_bf16_f32 %0, %1, %2" : "=v"(r) : "v"(lo), "v"(hi)); return r; }
;     __device__ __forceinline__ void operator()(const f32x4 (&acc)[2][2][4][2], const Unit& u, int wr, int wc, int fr, int fq) const {
;     ...
;             for (int m = 0; m < 4; ++m) {
;                 const int row = row0 + ai * HALF + m * 16; const size_t off = (size_t)row * 1024 + col0; float ss = 0.f;
; #pragma unroll
;                 for (int bj = 0; bj < 2; ++bj) {
;                     const u32x4 w = pre[m][bj];
;                     f32x4 v0 = acc[ai][bj][m][0], v1 = acc[ai][bj][m][1];
;                     v0[0] += __uint_as_float(w.x << 16); v0[1] += __uint_as_float(w.x & 0xffff0000u); v0[2] += __uint_as_float(w.y << 16); v0[3] += __uint_as_float(w.y & 0xffff0000u);
;                     v1[0] += __uint_as_float(w.z << 16); v1[1] += __uint_as_float(w.z & 0xffff0000u); v1[2] += __uint_as_float(w.w << 16); v1[3] += __uint_as_float(w.w & 0xffff0000u);
;                     if (outf) { *(f32x4*)(outf + off + bj * HALF) = v0; *(f32x4*)(outf + off + bj * HALF + 4) = v1; }
;                     else {
;                         ss += ((v0[0] * v0[0] + v0[1] * v0[1]) + (v0[2] * v0[2] + v0[3] * v0[3])) + ((v1[0] * v1[0] + v1[1] * v1[1]) + (v1[2] * v1[2] + v1[3] * v1[3]));
;                         u32x4 o; o.x = cvt_pk_bf16(v0[0], v0[1]); o.y = cvt_pk_bf16(v0[2], v0[3]); o.z = cvt_pk_bf16(v1[0], v1[1]); o.w = cvt_pk_bf16(v1[2], v1[3]);
;                         *(u32x4*)(xb + off + bj * HALF) = o;
;                     }
;                 }
;                 if (!outf) { ss += __shfl_xor(ss, 16); ss += __shfl_xor(ss, 32); if (fq == 0) rowsq[(size_t)row * 16 + u.pn * 4 + wc] = ss; }
.LBB0_571:
	s_or_b64 exec, exec, s[34:35]
	v_lshlrev_b32_e32 v48, 16, v224
	v_add_f32_e32 v44, v44, v48
	v_and_b32_e32 v48, 0xffff0000, v224
	v_add_f32_e32 v45, v45, v48
	v_lshlrev_b32_e32 v48, 16, v225
	v_add_f32_e32 v46, v46, v48
	v_and_b32_e32 v48, 0xffff0000, v225
	v_add_f32_e32 v47, v47, v48
	v_lshlrev_b32_e32 v48, 16, v226
	v_add_f32_e32 v48, v40, v48
	v_and_b32_e32 v40, 0xffff0000, v226
	s_waitcnt lgkmcnt(0)
	v_add_f32_e32 v49, v41, v40
	v_lshlrev_b32_e32 v40, 16, v227
	v_add_f32_e32 v50, v42, v40
	v_and_b32_e32 v40, 0xffff0000, v227
	v_add_f32_e32 v43, v43, v40
	v_mul_f32_e32 v40, v45, v45
	v_mul_f32_e32 v41, v47, v47
	v_fmac_f32_e32 v40, v44, v44
	v_fmac_f32_e32 v41, v46, v46
	v_add_f32_e32 v40, v40, v41
	v_mul_f32_e32 v41, v49, v49
	v_mul_f32_e32 v42, v43, v43
	v_fmac_f32_e32 v41, v48, v48
	v_fmac_f32_e32 v42, v50, v50
	v_add_f32_e32 v41, v41, v42
	v_add_f32_e32 v51, v40, v41
	v_cvt_pk_bf16_f32 v40, v44, v45
	v_lshlrev_b32_e32 v44, 16, v228
	v_add_f32_e32 v36, v36, v44
	v_and_b32_e32 v44, 0xffff0000, v228
	v_add_f32_e32 v37, v37, v44
	v_lshlrev_b32_e32 v44, 16, v229
	v_add_f32_e32 v44, v38, v44
	v_and_b32_e32 v38, 0xffff0000, v229
	v_add_f32_e32 v45, v39, v38
	v_lshlrev_b32_e32 v38, 16, v230
	v_cvt_pk_bf16_f32 v41, v46, v47
	v_add_f32_e32 v46, v32, v38
	v_and_b32_e32 v32, 0xffff0000, v230
	v_add_f32_e32 v47, v33, v32
	v_lshlrev_b32_e32 v32, 16, v231
	v_cvt_pk_bf16_f32 v42, v48, v49
	v_add_f32_e32 v48, v34, v32
	v_and_b32_e32 v32, 0xffff0000, v231
	v_add_f32_e32 v49, v35, v32
	v_mul_f32_e32 v32, v37, v37
	v_mul_f32_e32 v33, v45, v45
	v_fmac_f32_e32 v32, v36, v36
	v_fmac_f32_e32 v33, v44, v44
	v_add_f32_e32 v32, v32, v33
	v_mul_f32_e32 v33, v47, v47
	v_mul_f32_e32 v34, v49, v49
	v_fmac_f32_e32 v33, v46, v46
	v_fmac_f32_e32 v34, v48, v48
	v_add_f32_e32 v33, v33, v34
	v_add_f32_e32 v32, v32, v33
	v_add_f32_e32 v35, v51, v32
	v_cvt_pk_bf16_f32 v43, v50, v43
	ds_bpermute_b32 v50, v136, v35
	v_lshl_add_u64 v[32:33], s[8:9], 0, v[102:103]
	v_lshl_add_u64 v[38:39], v[164:165], 1, v[32:33]
	flat_store_dwordx4 v[38:39], v[40:43]
	v_cvt_pk_bf16_f32 v34, v36, v37
	s_waitcnt lgkmcnt(0)
	v_add_f32_e32 v32, v35, v50
	v_mov_b32_e32 v33, v32
	s_nop 1
	v_permlane32_swap_b32_e32 v32, v33
	v_cvt_pk_bf16_f32 v35, v44, v45
	v_cvt_pk_bf16_f32 v36, v46, v47
	v_cvt_pk_bf16_f32 v37, v48, v49
	flat_store_dwordx4 v[38:39], v[34:37] offset:256
	s_and_saveexec_b64 s[34:35], s[0:1]
	s_cbranch_execz .LBB0_573
	v_lshlrev_b64 v[34:35], 6, v[100:101]
	v_readlane_b32 s14, v254, 24
	v_lshl_add_u64 v[34:35], s[16:17], 0, v[34:35]
	v_readlane_b32 s15, v254, 25
	v_lshl_add_u64 v[34:35], s[48:49], 2, v[34:35]
	s_mov_b32 s19, s15
	s_lshl_b32 s18, s25, 2
	v_writelane_b32 v254, s14, 24
	v_lshl_add_u64 v[34:35], v[34:35], 0, s[18:19]
	s_waitcnt lgkmcnt(0)
	v_add_f32_e32 v32, v32, v33
	v_writelane_b32 v254, s15, 25
	flat_store_dword v[34:35], v32
; __device__ __forceinline__ unsigned cvt_pk_bf16(float lo, float hi) { unsigned r; asm volatile("v_cvt_pk_bf16_f32 %0, %1, %2" : "=v"(r) : "v"(lo), "v"(hi)); return r; }
;     __device__ __forceinline__ void operator()(const f32x4 (&acc)[2][2][4][2], const Unit& u, int wr, int wc, int fr, int fq) const {
;     ...
;             for (int m = 0; m < 4; ++m) {
;                 const int row = row0 + ai * HALF + m * 16; const size_t off = (size_t)row * 1024 + col0; float ss = 0.f;
; #pragma unroll
;                 for (int bj = 0; bj < 2; ++bj) {
;                     const u32x4 w = pre[m][bj];
;                     f32x4 v0 = acc[ai][bj][m][0], v1 = acc[ai][bj][m][1];
;                     v0[0] += __uint_as_float(w.x << 16); v0[1] += __uint_as_float(w.x & 0xffff0000u); v0[2] += __uint_as_float(w.y << 16); v0[3] += __uint_as_float(w.y & 0xffff0000u);
;                     v1[0] += __uint_as_float(w.z << 16); v1[1] += __uint_as_float(w.z & 0xffff0000u); v1[2] += __uint_as_float(w.w << 16); v1[3] += __uint_as_float(w.w & 0xffff0000u);
;                     if (outf) { *(f32x4*)(outf + off + bj * HALF) = v0; *(f32x4*)(outf + off + bj * HALF + 4) = v1; }
;                     else {
;                         ss += ((v0[0] * v0[0] + v0[1] * v0[1]) + (v0[2] * v0[2] + v0[3] * v0[3])) + ((v1[0] * v1[0] + v1[1] * v1[1]) + (v1[2] * v1[2] + v1[3] * v1[3]));
;                         u32x4 o; o.x = cvt_pk_bf16(v0[0], v0[1]); o.y = cvt_pk_bf16(v0[2], v0[3]); o.z = cvt_pk_bf16(v1[0], v1[1]); o.w = cvt_pk_bf16(v1[2], v1[3]);
;                         *(u32x4*)(xb + off + bj * HALF) = o;
;                     }
;                 }
;                 if (!outf) { ss += __shfl_xor(ss, 16); ss += __shfl_xor(ss, 32); if (fq == 0) rowsq[(size_t)row * 16 + u.pn * 4 + wc] = ss; }
.LBB0_573:
	s_or_b64 exec, exec, s[34:35]
	v_lshlrev_b32_e32 v32, 16, v232
	v_add_f32_e32 v28, v28, v32
	v_and_b32_e32 v32, 0xffff0000, v232
	v_add_f32_e32 v29, v29, v32
	v_lshlrev_b32_e32 v32, 16, v233
	v_add_f32_e32 v30, v30, v32
	v_and_b32_e32 v32, 0xffff0000, v233
	v_add_f32_e32 v31, v31, v32
	v_lshlrev_b32_e32 v32, 16, v234
	v_add_f32_e32 v32, v24, v32
	v_and_b32_e32 v24, 0xffff0000, v234
	s_waitcnt lgkmcnt(0)
	v_add_f32_e32 v33, v25, v24
	v_lshlrev_b32_e32 v24, 16, v235
	v_add_f32_e32 v34, v26, v24
	v_and_b32_e32 v24, 0xffff0000, v235
	v_add_f32_e32 v27, v27, v24
	v_mul_f32_e32 v24, v29, v29
	v_mul_f32_e32 v25, v31, v31
	v_fmac_f32_e32 v24, v28, v28
	v_fmac_f32_e32 v25, v30, v30
	v_add_f32_e32 v24, v24, v25
	v_mul_f32_e32 v25, v33, v33
	v_mul_f32_e32 v26, v27, v27
	v_fmac_f32_e32 v25, v32, v32
	v_fmac_f32_e32 v26, v34, v34
	v_add_f32_e32 v25, v25, v26
	v_add_f32_e32 v35, v24, v25
	v_cvt_pk_bf16_f32 v24, v28, v29
	v_lshlrev_b32_e32 v28, 16, v152
	v_add_f32_e32 v20, v20, v28
	v_and_b32_e32 v28, 0xffff0000, v152
	v_add_f32_e32 v21, v21, v28
	v_lshlrev_b32_e32 v28, 16, v153
	v_add_f32_e32 v28, v22, v28
	v_and_b32_e32 v22, 0xffff0000, v153
	v_add_f32_e32 v29, v23, v22
	v_lshlrev_b32_e32 v22, 16, v154
	v_cvt_pk_bf16_f32 v25, v30, v31
	v_add_f32_e32 v30, v16, v22
	v_and_b32_e32 v16, 0xffff0000, v154
	v_add_f32_e32 v31, v17, v16
	v_lshlrev_b32_e32 v16, 16, v155
	v_cvt_pk_bf16_f32 v26, v32, v33
	v_add_f32_e32 v32, v18, v16
	v_and_b32_e32 v16, 0xffff0000, v155
	v_add_f32_e32 v33, v19, v16
	v_mul_f32_e32 v16, v21, v21
	v_mul_f32_e32 v17, v29, v29
	v_fmac_f32_e32 v16, v20, v20
	v_fmac_f32_e32 v17, v28, v28
	v_add_f32_e32 v16, v16, v17
	v_mul_f32_e32 v17, v31, v31
	v_mul_f32_e32 v18, v33, v33
	v_fmac_f32_e32 v17, v30, v30
	v_fmac_f32_e32 v18, v32, v32
	v_add_f32_e32 v17, v17, v18
	v_add_f32_e32 v16, v16, v17
	v_add_f32_e32 v19, v35, v16
	v_cvt_pk_bf16_f32 v27, v34, v27
	ds_bpermute_b32 v34, v136, v19
	v_lshl_add_u64 v[16:17], s[8:9], 0, v[98:99]
	v_lshl_add_u64 v[22:23], v[164:165], 1, v[16:17]
	flat_store_dwordx4 v[22:23], v[24:27]
	v_cvt_pk_bf16_f32 v18, v20, v21
	s_waitcnt lgkmcnt(0)
	v_add_f32_e32 v16, v19, v34
	v_mov_b32_e32 v17, v16
	s_nop 1
	v_permlane32_swap_b32_e32 v16, v17
	v_cvt_pk_bf16_f32 v19, v28, v29
	v_cvt_pk_bf16_f32 v20, v30, v31
	v_cvt_pk_bf16_f32 v21, v32, v33
	flat_store_dwordx4 v[22:23], v[18:21] offset:256
	s_and_saveexec_b64 s[34:35], s[0:1]
	s_cbranch_execz .LBB0_575
	v_lshlrev_b64 v[18:19], 6, v[96:97]
	v_readlane_b32 s14, v254, 24
	v_lshl_add_u64 v[18:19], s[16:17], 0, v[18:19]
	v_readlane_b32 s15, v254, 25
	v_lshl_add_u64 v[18:19], s[48:49], 2, v[18:19]
	s_mov_b32 s19, s15
	s_lshl_b32 s18, s25, 2
	v_writelane_b32 v254, s14, 24
	v_lshl_add_u64 v[18:19], v[18:19], 0, s[18:19]
	s_waitcnt lgkmcnt(0)
	v_add_f32_e32 v16, v16, v17
	v_writelane_b32 v254, s15, 25
	flat_store_dword v[18:19], v16
.LBB0_575:
	s_or_b64 exec, exec, s[34:35]
	v_lshlrev_b32_e32 v16, 16, v156
	v_add_f32_e32 v12, v12, v16
	v_and_b32_e32 v16, 0xffff0000, v156
	v_add_f32_e32 v13, v13, v16
	v_lshlrev_b32_e32 v16, 16, v157
	v_add_f32_e32 v14, v14, v16
	v_and_b32_e32 v16, 0xffff0000, v157
	v_add_f32_e32 v15, v15, v16
	v_lshlrev_b32_e32 v16, 16, v158
	v_add_f32_e32 v16, v8, v16
	v_and_b32_e32 v8, 0xffff0000, v158
	s_waitcnt lgkmcnt(0)
	v_add_f32_e32 v17, v9, v8
	v_lshlrev_b32_e32 v8, 16, v159
	v_add_f32_e32 v18, v10, v8
	v_and_b32_e32 v8, 0xffff0000, v159
	v_add_f32_e32 v11, v11, v8
	v_mul_f32_e32 v8, v13, v13
	v_mul_f32_e32 v9, v15, v15
	v_fmac_f32_e32 v8, v12, v12
	v_fmac_f32_e32 v9, v14, v14
	v_add_f32_e32 v8, v8, v9
	v_mul_f32_e32 v9, v17, v17
	v_mul_f32_e32 v10, v11, v11
	v_fmac_f32_e32 v9, v16, v16
	v_fmac_f32_e32 v10, v18, v18
	v_add_f32_e32 v9, v9, v10
	v_add_f32_e32 v19, v8, v9
	v_cvt_pk_bf16_f32 v8, v12, v13
	v_lshlrev_b32_e32 v12, 16, v160
	v_add_f32_e32 v4, v4, v12
	v_and_b32_e32 v12, 0xffff0000, v160
	v_add_f32_e32 v5, v5, v12
	v_lshlrev_b32_e32 v12, 16, v161
	v_add_f32_e32 v12, v6, v12
	v_and_b32_e32 v6, 0xffff0000, v161
	v_add_f32_e32 v13, v7, v6
	v_lshlrev_b32_e32 v6, 16, v162
	v_cvt_pk_bf16_f32 v9, v14, v15
	v_add_f32_e32 v14, v0, v6
	v_and_b32_e32 v0, 0xffff0000, v162
	v_add_f32_e32 v15, v1, v0
	v_lshlrev_b32_e32 v0, 16, v163
	v_cvt_pk_bf16_f32 v10, v16, v17
	v_add_f32_e32 v16, v2, v0
	v_and_b32_e32 v0, 0xffff0000, v163
	v_add_f32_e32 v17, v3, v0
	v_mul_f32_e32 v0, v5, v5
	v_mul_f32_e32 v1, v13, v13
	v_fmac_f32_e32 v0, v4, v4
	v_fmac_f32_e32 v1, v12, v12
	v_add_f32_e32 v0, v0, v1
	v_mul_f32_e32 v1, v15, v15
	v_mul_f32_e32 v2, v17, v17
	v_fmac_f32_e32 v1, v14, v14
	v_fmac_f32_e32 v2, v16, v16
	v_add_f32_e32 v1, v1, v2
	v_add_f32_e32 v0, v0, v1
	v_add_f32_e32 v3, v19, v0
	v_cvt_pk_bf16_f32 v11, v18, v11
	ds_bpermute_b32 v18, v136, v3
	v_lshl_add_u64 v[0:1], s[8:9], 0, v[94:95]
	v_lshl_add_u64 v[6:7], v[164:165], 1, v[0:1]
	flat_store_dwordx4 v[6:7], v[8:11]
	v_cvt_pk_bf16_f32 v2, v4, v5
	s_waitcnt lgkmcnt(0)
	v_add_f32_e32 v0, v3, v18
	v_mov_b32_e32 v1, v0
	s_nop 1
	v_permlane32_swap_b32_e32 v0, v1
	v_cvt_pk_bf16_f32 v3, v12, v13
	v_cvt_pk_bf16_f32 v4, v14, v15
	v_cvt_pk_bf16_f32 v5, v16, v17
	flat_store_dwordx4 v[6:7], v[2:5] offset:256
	s_and_saveexec_b64 s[34:35], s[0:1]
	s_cbranch_execz .LBB0_577
	v_lshlrev_b64 v[2:3], 6, v[92:93]
	v_readlane_b32 s14, v254, 24
	v_lshl_add_u64 v[2:3], s[16:17], 0, v[2:3]
	v_readlane_b32 s15, v254, 25
	v_lshl_add_u64 v[2:3], s[48:49], 2, v[2:3]
	s_mov_b32 s19, s15
	s_lshl_b32 s18, s25, 2
	v_writelane_b32 v254, s14, 24
	v_lshl_add_u64 v[2:3], v[2:3], 0, s[18:19]
	s_waitcnt lgkmcnt(0)
	v_add_f32_e32 v0, v0, v1
	v_writelane_b32 v254, s15, 25
	flat_store_dword v[2:3], v0

;     __device__ __forceinline__ void operator()(const f32x4 (&acc)[2][2][4][2], const Unit& u, int wr, int wc, int fr, int fq) const {
;     ...
;                 if (!outf) { ss += __shfl_xor(ss, 16); ss += __shfl_xor(ss, 32); if (fq == 0) rowsq[(size_t)row * 16 + u.pn * 4 + wc] = ss; }
.LBB0_755:
	s_lshl_b32 s56, s14, 2
	v_cndmask_b32_e64 v112, 0, 1, s[44:45]
	v_cmp_ne_u32_e64 s[38:39], 1, v112
	s_andn2_b64 vcc, exec, s[44:45]
	s_ashr_i32 s57, s56, 31
	s_cbranch_vccnz .LBB0_759
	v_and_b32_e32 v113, 64, v244
	v_xor_b32_e32 v112, 16, v244
	v_add_u32_e32 v113, 64, v113
	v_cmp_lt_i32_e32 vcc, v112, v113
	v_xor_b32_e32 v114, 32, v244
	s_nop 0
	v_cndmask_b32_e32 v112, v244, v112, vcc
	v_lshlrev_b32_e32 v112, 2, v112
	ds_bpermute_b32 v112, v112, v178
	v_cmp_lt_i32_e32 vcc, v114, v113
	s_waitcnt lgkmcnt(0)
	v_add_f32_e32 v112, v178, v112
	v_cndmask_b32_e32 v113, v244, v114, vcc
	v_lshlrev_b32_e32 v113, 2, v113
	v_mov_b32_e32 v113, v112
	s_nop 1
	v_permlane32_swap_b32_e32 v112, v113
	s_and_saveexec_b64 s[34:35], s[0:1]
	s_cbranch_execz .LBB0_758
	v_lshlrev_b64 v[114:115], 6, v[172:173]
	v_readlane_b32 s14, v254, 24
	v_lshl_add_u64 v[114:115], s[26:27], 0, v[114:115]
	v_readlane_b32 s15, v254, 25
	v_lshl_add_u64 v[114:115], s[56:57], 2, v[114:115]
	s_mov_b32 s19, s15
	s_lshl_b32 s18, s28, 2
	v_writelane_b32 v254, s14, 24
	v_lshl_add_u64 v[114:115], v[114:115], 0, s[18:19]
	s_waitcnt lgkmcnt(0)
	v_add_f32_e32 v112, v112, v113
	v_writelane_b32 v254, s15, 25
	flat_store_dword v[114:115], v112

;     __device__ __forceinline__ void operator()(const f32x4 (&acc)[2][2][4][2], const Unit& u, int wr, int wc, int fr, int fq) const {
;     ...
;                 if (!outf) { ss += __shfl_xor(ss, 16); ss += __shfl_xor(ss, 32); if (fq == 0) rowsq[(size_t)row * 16 + u.pn * 4 + wc] = ss; }
.LBB0_768:
	v_and_b32_e32 v97, 64, v244
	v_xor_b32_e32 v96, 16, v244
	v_add_u32_e32 v97, 64, v97
	v_cmp_lt_i32_e32 vcc, v96, v97
	v_xor_b32_e32 v98, 32, v244
	s_nop 0
	v_cndmask_b32_e32 v96, v244, v96, vcc
	v_lshlrev_b32_e32 v96, 2, v96
	ds_bpermute_b32 v96, v96, v118
	v_cmp_lt_i32_e32 vcc, v98, v97
	s_waitcnt lgkmcnt(0)
	v_add_f32_e32 v96, v118, v96
	v_cndmask_b32_e32 v97, v244, v98, vcc
	v_lshlrev_b32_e32 v97, 2, v97
	v_mov_b32_e32 v97, v96
	s_nop 1
	v_permlane32_swap_b32_e32 v96, v97
	s_and_saveexec_b64 s[34:35], s[0:1]
	s_cbranch_execz .LBB0_770
	v_lshlrev_b64 v[98:99], 6, v[196:197]
	v_readlane_b32 s14, v254, 24
	v_lshl_add_u64 v[98:99], s[26:27], 0, v[98:99]
	v_readlane_b32 s15, v254, 25
	v_lshl_add_u64 v[98:99], s[56:57], 2, v[98:99]
	s_mov_b32 s19, s15
	s_lshl_b32 s18, s28, 2
	v_writelane_b32 v254, s14, 24
	v_lshl_add_u64 v[98:99], v[98:99], 0, s[18:19]
	s_waitcnt lgkmcnt(0)
	v_add_f32_e32 v96, v96, v97
	v_writelane_b32 v254, s15, 25
	flat_store_dword v[98:99], v96

;     __device__ __forceinline__ void operator()(const f32x4 (&acc)[2][2][4][2], const Unit& u, int wr, int wc, int fr, int fq) const {
;     ...
;                 if (!outf) { ss += __shfl_xor(ss, 16); ss += __shfl_xor(ss, 32); if (fq == 0) rowsq[(size_t)row * 16 + u.pn * 4 + wc] = ss; }
.LBB0_780:
	v_and_b32_e32 v81, 64, v244
	v_xor_b32_e32 v80, 16, v244
	v_add_u32_e32 v81, 64, v81
	v_cmp_lt_i32_e32 vcc, v80, v81
	v_xor_b32_e32 v82, 32, v244
	s_nop 0
	v_cndmask_b32_e32 v80, v244, v80, vcc
	v_lshlrev_b32_e32 v80, 2, v80
	ds_bpermute_b32 v80, v80, v102
	v_cmp_lt_i32_e32 vcc, v82, v81
	s_waitcnt lgkmcnt(0)
	v_add_f32_e32 v80, v102, v80
	v_cndmask_b32_e32 v81, v244, v82, vcc
	v_lshlrev_b32_e32 v81, 2, v81
	v_mov_b32_e32 v81, v80
	s_nop 1
	v_permlane32_swap_b32_e32 v80, v81
	s_and_saveexec_b64 s[34:35], s[0:1]
	s_cbranch_execz .LBB0_782
	v_lshlrev_b64 v[82:83], 6, v[194:195]
	v_readlane_b32 s14, v254, 24
	v_lshl_add_u64 v[82:83], s[26:27], 0, v[82:83]
	v_readlane_b32 s15, v254, 25
	v_lshl_add_u64 v[82:83], s[56:57], 2, v[82:83]
	s_mov_b32 s19, s15
	s_lshl_b32 s18, s28, 2
	v_writelane_b32 v254, s14, 24
	v_lshl_add_u64 v[82:83], v[82:83], 0, s[18:19]
	s_waitcnt lgkmcnt(0)
	v_add_f32_e32 v80, v80, v81
	v_writelane_b32 v254, s15, 25
	flat_store_dword v[82:83], v80

;     __device__ __forceinline__ void operator()(const f32x4 (&acc)[2][2][4][2], const Unit& u, int wr, int wc, int fr, int fq) const {
;     ...
;                 if (!outf) { ss += __shfl_xor(ss, 16); ss += __shfl_xor(ss, 32); if (fq == 0) rowsq[(size_t)row * 16 + u.pn * 4 + wc] = ss; }
.LBB0_792:
	v_and_b32_e32 v65, 64, v244
	v_xor_b32_e32 v64, 16, v244
	v_add_u32_e32 v65, 64, v65
	v_cmp_lt_i32_e32 vcc, v64, v65
	v_xor_b32_e32 v66, 32, v244
	s_nop 0
	v_cndmask_b32_e32 v64, v244, v64, vcc
	v_lshlrev_b32_e32 v64, 2, v64
	ds_bpermute_b32 v64, v64, v86
	v_cmp_lt_i32_e32 vcc, v66, v65
	s_waitcnt lgkmcnt(0)
	v_add_f32_e32 v64, v86, v64
	v_cndmask_b32_e32 v65, v244, v66, vcc
	v_lshlrev_b32_e32 v65, 2, v65
	v_mov_b32_e32 v65, v64
	s_nop 1
	v_permlane32_swap_b32_e32 v64, v65
	s_and_saveexec_b64 s[34:35], s[0:1]
	s_cbranch_execz .LBB0_794
	v_lshlrev_b64 v[66:67], 6, v[174:175]
	v_readlane_b32 s14, v254, 24
	v_lshl_add_u64 v[66:67], s[26:27], 0, v[66:67]
	v_readlane_b32 s15, v254, 25
	v_lshl_add_u64 v[66:67], s[56:57], 2, v[66:67]
	s_mov_b32 s19, s15
	s_lshl_b32 s18, s28, 2
	v_writelane_b32 v254, s14, 24
	v_lshl_add_u64 v[66:67], v[66:67], 0, s[18:19]
	s_waitcnt lgkmcnt(0)
	v_add_f32_e32 v64, v64, v65
	v_writelane_b32 v254, s15, 25
	flat_store_dword v[66:67], v64

;     __device__ __forceinline__ void operator()(const f32x4 (&acc)[2][2][4][2], const Unit& u, int wr, int wc, int fr, int fq) const {
;     ...
;                 if (!outf) { ss += __shfl_xor(ss, 16); ss += __shfl_xor(ss, 32); if (fq == 0) rowsq[(size_t)row * 16 + u.pn * 4 + wc] = ss; }
.LBB0_804:
	v_and_b32_e32 v49, 64, v244
	v_xor_b32_e32 v48, 16, v244
	v_add_u32_e32 v49, 64, v49
	v_cmp_lt_i32_e32 vcc, v48, v49
	v_xor_b32_e32 v50, 32, v244
	s_nop 0
	v_cndmask_b32_e32 v48, v244, v48, vcc
	v_lshlrev_b32_e32 v48, 2, v48
	ds_bpermute_b32 v48, v48, v106
	v_cmp_lt_i32_e32 vcc, v50, v49
	s_waitcnt lgkmcnt(0)
	v_add_f32_e32 v48, v106, v48
	v_cndmask_b32_e32 v49, v244, v50, vcc
	v_lshlrev_b32_e32 v49, 2, v49
	v_mov_b32_e32 v49, v48
	s_nop 1
	v_permlane32_swap_b32_e32 v48, v49
	s_and_saveexec_b64 s[34:35], s[0:1]
	s_cbranch_execz .LBB0_806
	v_lshlrev_b64 v[50:51], 6, v[98:99]
	v_readlane_b32 s14, v254, 24
	v_lshl_add_u64 v[50:51], s[26:27], 0, v[50:51]
	v_readlane_b32 s15, v254, 25
	v_lshl_add_u64 v[50:51], s[56:57], 2, v[50:51]
	s_mov_b32 s19, s15
	s_lshl_b32 s18, s28, 2
	v_writelane_b32 v254, s14, 24
	v_lshl_add_u64 v[50:51], v[50:51], 0, s[18:19]
	s_waitcnt lgkmcnt(0)
	v_add_f32_e32 v48, v48, v49
	v_writelane_b32 v254, s15, 25
	flat_store_dword v[50:51], v48

;     __device__ __forceinline__ void operator()(const f32x4 (&acc)[2][2][4][2], const Unit& u, int wr, int wc, int fr, int fq) const {
;     ...
;                 if (!outf) { ss += __shfl_xor(ss, 16); ss += __shfl_xor(ss, 32); if (fq == 0) rowsq[(size_t)row * 16 + u.pn * 4 + wc] = ss; }
.LBB0_816:
	v_and_b32_e32 v33, 64, v244
	v_xor_b32_e32 v32, 16, v244
	v_add_u32_e32 v33, 64, v33
	v_cmp_lt_i32_e32 vcc, v32, v33
	v_xor_b32_e32 v34, 32, v244
	s_nop 0
	v_cndmask_b32_e32 v32, v244, v32, vcc
	v_lshlrev_b32_e32 v32, 2, v32
	ds_bpermute_b32 v32, v32, v54
	v_cmp_lt_i32_e32 vcc, v34, v33
	s_waitcnt lgkmcnt(0)
	v_add_f32_e32 v32, v54, v32
	v_cndmask_b32_e32 v33, v244, v34, vcc
	v_lshlrev_b32_e32 v33, 2, v33
	v_mov_b32_e32 v33, v32
	s_nop 1
	v_permlane32_swap_b32_e32 v32, v33
	s_and_saveexec_b64 s[34:35], s[0:1]
	s_cbranch_execz .LBB0_818
	v_lshlrev_b64 v[34:35], 6, v[96:97]
	v_readlane_b32 s14, v254, 24
	v_lshl_add_u64 v[34:35], s[26:27], 0, v[34:35]
	v_readlane_b32 s15, v254, 25
	v_lshl_add_u64 v[34:35], s[56:57], 2, v[34:35]
	s_mov_b32 s19, s15
	s_lshl_b32 s18, s28, 2
	v_writelane_b32 v254, s14, 24
	v_lshl_add_u64 v[34:35], v[34:35], 0, s[18:19]
	s_waitcnt lgkmcnt(0)
	v_add_f32_e32 v32, v32, v33
	v_writelane_b32 v254, s15, 25
	flat_store_dword v[34:35], v32

;     __device__ __forceinline__ void operator()(const f32x4 (&acc)[2][2][4][2], const Unit& u, int wr, int wc, int fr, int fq) const {
;     ...
;                 if (!outf) { ss += __shfl_xor(ss, 16); ss += __shfl_xor(ss, 32); if (fq == 0) rowsq[(size_t)row * 16 + u.pn * 4 + wc] = ss; }
.LBB0_828:
	v_and_b32_e32 v17, 64, v244
	v_xor_b32_e32 v16, 16, v244
	v_add_u32_e32 v17, 64, v17
	v_cmp_lt_i32_e32 vcc, v16, v17
	v_xor_b32_e32 v18, 32, v244
	s_nop 0
	v_cndmask_b32_e32 v16, v244, v16, vcc
	v_lshlrev_b32_e32 v16, 2, v16
	ds_bpermute_b32 v16, v16, v38
	v_cmp_lt_i32_e32 vcc, v18, v17
	s_waitcnt lgkmcnt(0)
	v_add_f32_e32 v16, v38, v16
	v_cndmask_b32_e32 v17, v244, v18, vcc
	v_lshlrev_b32_e32 v17, 2, v17
	v_mov_b32_e32 v17, v16
	s_nop 1
	v_permlane32_swap_b32_e32 v16, v17
	s_and_saveexec_b64 s[34:35], s[0:1]
	s_cbranch_execz .LBB0_830
	v_lshlrev_b64 v[18:19], 6, v[94:95]
	v_readlane_b32 s14, v254, 24
	v_lshl_add_u64 v[18:19], s[26:27], 0, v[18:19]
	v_readlane_b32 s15, v254, 25
	v_lshl_add_u64 v[18:19], s[56:57], 2, v[18:19]
	s_mov_b32 s19, s15
	s_lshl_b32 s18, s28, 2
	v_writelane_b32 v254, s14, 24
	v_lshl_add_u64 v[18:19], v[18:19], 0, s[18:19]
	s_waitcnt lgkmcnt(0)
	v_add_f32_e32 v16, v16, v17
	v_writelane_b32 v254, s15, 25
	flat_store_dword v[18:19], v16

;     __device__ __forceinline__ void operator()(const f32x4 (&acc)[2][2][4][2], const Unit& u, int wr, int wc, int fr, int fq) const {
;     ...
;                 if (!outf) { ss += __shfl_xor(ss, 16); ss += __shfl_xor(ss, 32); if (fq == 0) rowsq[(size_t)row * 16 + u.pn * 4 + wc] = ss; }
.LBB0_840:
	v_and_b32_e32 v1, 64, v244
	v_xor_b32_e32 v0, 16, v244
	v_add_u32_e32 v1, 64, v1
	v_cmp_lt_i32_e32 vcc, v0, v1
	v_xor_b32_e32 v2, 32, v244
	s_nop 0
	v_cndmask_b32_e32 v0, v244, v0, vcc
	v_lshlrev_b32_e32 v0, 2, v0
	ds_bpermute_b32 v0, v0, v22
	v_cmp_lt_i32_e32 vcc, v2, v1
	s_waitcnt lgkmcnt(0)
	v_add_f32_e32 v0, v22, v0
	v_cndmask_b32_e32 v1, v244, v2, vcc
	v_lshlrev_b32_e32 v1, 2, v1
	v_mov_b32_e32 v1, v0
	s_nop 1
	v_permlane32_swap_b32_e32 v0, v1
	s_and_saveexec_b64 s[4:5], s[0:1]
	s_cbranch_execz .LBB0_842
	v_lshlrev_b64 v[2:3], 6, v[92:93]
	v_readlane_b32 s14, v254, 24
	v_lshl_add_u64 v[2:3], s[26:27], 0, v[2:3]
	v_readlane_b32 s15, v254, 25
	v_lshl_add_u64 v[2:3], s[56:57], 2, v[2:3]
	s_mov_b32 s19, s15
	s_lshl_b32 s18, s28, 2
	v_writelane_b32 v254, s14, 24
	v_lshl_add_u64 v[2:3], v[2:3], 0, s[18:19]
	s_waitcnt lgkmcnt(0)
	v_add_f32_e32 v0, v0, v1
	v_writelane_b32 v254, s15, 25
	flat_store_dword v[2:3], v0
